# zero-initialised leader clock slots so followers pace from the first unit
# speedup vs baseline: 1.1717x; 1.0092x over previous
_Z17hybrid_megakernel6Params:
	s_load_dwordx16 s[4:19], s[0:1], 0x0
	s_mov_b32 s60, s2
	v_and_b32_e32 v208, 0x3ff, v0
	v_or_b32_e32 v1, s60, v208
	v_cmp_eq_u32_e32 vcc, 0, v1
	s_waitcnt lgkmcnt(0)
	v_writelane_b32 v254, s4, 0
	s_nop 1
	v_writelane_b32 v254, s5, 1
	v_writelane_b32 v254, s6, 2
	v_writelane_b32 v254, s7, 3
	v_writelane_b32 v254, s8, 4
	v_writelane_b32 v254, s9, 5
	v_writelane_b32 v254, s10, 6
	v_writelane_b32 v254, s11, 7
	v_writelane_b32 v254, s12, 8
	v_writelane_b32 v254, s13, 9
	v_writelane_b32 v254, s14, 10
	v_writelane_b32 v254, s15, 11
	v_writelane_b32 v254, s16, 12
	v_writelane_b32 v254, s17, 13
	v_writelane_b32 v254, s18, 14
	v_writelane_b32 v254, s19, 15
	s_load_dwordx16 s[4:19], s[0:1], 0x40
	s_waitcnt lgkmcnt(0)
	v_writelane_b32 v254, s4, 16
	s_nop 1
	v_writelane_b32 v254, s5, 17
	v_writelane_b32 v254, s6, 18
	v_writelane_b32 v254, s7, 19
	v_writelane_b32 v254, s8, 20
	v_writelane_b32 v254, s9, 21
	v_writelane_b32 v254, s10, 22
	v_writelane_b32 v254, s11, 23
	v_writelane_b32 v254, s12, 24
	v_writelane_b32 v254, s13, 25
	v_writelane_b32 v254, s14, 26
	v_writelane_b32 v254, s15, 27
	v_writelane_b32 v254, s16, 28
	v_writelane_b32 v254, s17, 29
	v_writelane_b32 v254, s18, 30
	v_writelane_b32 v254, s19, 31
	s_load_dwordx2 s[92:93], s[0:1], 0x90
	s_load_dwordx4 s[4:7], s[0:1], 0x80
	s_load_dword s95, s[0:1], 0x98
	s_add_u32 s14, s0, 0x98
	s_addc_u32 s15, s1, 0
	s_waitcnt lgkmcnt(0)
	v_writelane_b32 v254, s4, 32
	s_nop 1
	v_writelane_b32 v254, s5, 33
	v_writelane_b32 v254, s6, 34
	v_writelane_b32 v254, s7, 35
	s_add_u32 s4, s92, 0x36f08000
	s_addc_u32 s5, s93, 0
	s_and_saveexec_b64 s[0:1], vcc
	s_cbranch_execz .LBB0_2
	v_mov_b32_e32 v1, 0
	global_store_dword v1, v1, s[4:5] sc1
	global_store_dword v1, v1, s[4:5] offset:2048 sc1
	global_store_dword v1, v1, s[4:5] offset:2176 sc1
	global_store_dword v1, v1, s[4:5] offset:2304 sc1
	global_store_dword v1, v1, s[4:5] offset:2432 sc1
	global_store_dword v1, v1, s[4:5] offset:2560 sc1
	global_store_dword v1, v1, s[4:5] offset:2688 sc1
	global_store_dword v1, v1, s[4:5] offset:2816 sc1
	global_store_dword v1, v1, s[4:5] offset:2944 sc1
	global_store_dword v1, v1, s[4:5] offset:256 sc1
	global_store_dword v1, v1, s[4:5] offset:384 sc1
	global_store_dword v1, v1, s[4:5] offset:512 sc1
	global_store_dword v1, v1, s[4:5] offset:640 sc1
	global_store_dword v1, v1, s[4:5] offset:768 sc1
	global_store_dword v1, v1, s[4:5] offset:896 sc1
	global_store_dword v1, v1, s[4:5] offset:1024 sc1
	global_store_dword v1, v1, s[4:5] offset:1152 sc1
